# hand-written software-pipelined GDN chunk-state scan (double-buffered operand prefetch, counted vmcnt) replacing the serialized compiler loop
# speedup vs baseline: 1.0045x; 1.0045x over previous
.LBB0_478:
	s_andn2_b64 vcc, exec, s[0:1]
	s_cbranch_vccnz .LBB0_483
	s_setprio 2
	v_readlane_b32 s0, v247, 39
	s_cmpk_gt_i32 s0, 0xff
	v_readlane_b32 s1, v247, 40
	s_cbranch_scc1 .LBB0_482
	s_waitcnt vmcnt(0) lgkmcnt(0)
	v_and_b32_e32 v1, 63, v0
	v_lshlrev_b32_e32 v101, 4, v1
	ds_write_b128 v101, v[124:127]
	ds_write_b128 v101, v[128:131] offset:1024
	ds_write_b128 v101, v[132:135] offset:2048
	ds_write_b128 v101, v[136:139] offset:3072
	ds_write_b128 v101, v[140:143] offset:4096
	ds_write_b128 v101, v[144:147] offset:5120
	ds_write_b128 v101, v[148:151] offset:6144
	ds_write_b128 v101, v[152:155] offset:7168
	ds_write_b128 v101, v[156:159] offset:8192
	ds_write_b128 v101, v[160:163] offset:9216
	ds_write_b128 v101, v[164:167] offset:10240
	ds_write_b128 v101, v[168:171] offset:11264
	ds_write_b128 v101, v[172:175] offset:12288
	ds_write_b128 v101, v[176:179] offset:13312
	ds_write_b128 v101, v[180:183] offset:14336
	ds_write_b128 v101, v[184:187] offset:15360
	s_ashr_i32 s0, s88, 2
	s_and_b32 s1, s88, 3
	s_lshl_b32 s0, s0, 20
	s_add_u32 s4, s94, 0x66d00000
	s_addc_u32 s5, s95, 0
	s_add_u32 s4, s4, s0
	s_addc_u32 s5, s5, 0
	s_add_u32 s6, s94, 0x74500000
	s_addc_u32 s7, s95, 0
	s_add_u32 s6, s6, s0
	s_addc_u32 s7, s7, 0
	s_add_u32 s8, s94, 0x62d00000
	s_addc_u32 s9, s95, 0
	s_add_u32 s8, s8, s0
	s_addc_u32 s9, s9, 0
	v_and_b32_e32 v98, 31, v1
	v_lshlrev_b32_e32 v98, 8, v98
	v_lshrrev_b32_e32 v99, 5, v1
	v_lshl_or_b32 v98, v99, 4, v98
	s_lshl_b32 s10, s1, 11
	v_lshl_or_b32 v99, v1, 3, s10
	s_lshl_b32 s10, s1, 13
	s_add_u32 s10, s10, 0x1000
	v_lshl_add_u32 v100, v1, 4, s10
	v_mov_b32_e32 v2, 0
	v_mov_b32_e32 v3, 0
	v_mov_b32_e32 v4, 0
	v_mov_b32_e32 v5, 0
	v_mov_b32_e32 v6, 0
	v_mov_b32_e32 v7, 0
	v_mov_b32_e32 v8, 0
	v_mov_b32_e32 v9, 0
	v_mov_b32_e32 v10, 0
	v_mov_b32_e32 v11, 0
	v_mov_b32_e32 v12, 0
	v_mov_b32_e32 v13, 0
	v_mov_b32_e32 v14, 0
	v_mov_b32_e32 v15, 0
	v_mov_b32_e32 v16, 0
	v_mov_b32_e32 v17, 0
	v_mov_b32_e32 v18, 0
	v_mov_b32_e32 v19, 0
	v_mov_b32_e32 v20, 0
	v_mov_b32_e32 v21, 0
	v_mov_b32_e32 v22, 0
	v_mov_b32_e32 v23, 0
	v_mov_b32_e32 v24, 0
	v_mov_b32_e32 v25, 0
	v_mov_b32_e32 v26, 0
	v_mov_b32_e32 v27, 0
	v_mov_b32_e32 v28, 0
	v_mov_b32_e32 v29, 0
	v_mov_b32_e32 v30, 0
	v_mov_b32_e32 v31, 0
	v_mov_b32_e32 v32, 0
	v_mov_b32_e32 v33, 0
	v_mov_b32_e32 v34, 0
	v_mov_b32_e32 v35, 0
	v_mov_b32_e32 v36, 0
	v_mov_b32_e32 v37, 0
	v_mov_b32_e32 v38, 0
	v_mov_b32_e32 v39, 0
	v_mov_b32_e32 v40, 0
	v_mov_b32_e32 v41, 0
	v_mov_b32_e32 v42, 0
	v_mov_b32_e32 v43, 0
	v_mov_b32_e32 v44, 0
	v_mov_b32_e32 v45, 0
	v_mov_b32_e32 v46, 0
	v_mov_b32_e32 v47, 0
	v_mov_b32_e32 v48, 0
	v_mov_b32_e32 v49, 0
	v_mov_b32_e32 v50, 0
	v_mov_b32_e32 v51, 0
	v_mov_b32_e32 v52, 0
	v_mov_b32_e32 v53, 0
	v_mov_b32_e32 v54, 0
	v_mov_b32_e32 v55, 0
	v_mov_b32_e32 v56, 0
	v_mov_b32_e32 v57, 0
	v_mov_b32_e32 v58, 0
	v_mov_b32_e32 v59, 0
	v_mov_b32_e32 v60, 0
	v_mov_b32_e32 v61, 0
	v_mov_b32_e32 v62, 0
	v_mov_b32_e32 v63, 0
	v_mov_b32_e32 v64, 0
	v_mov_b32_e32 v65, 0
	s_mov_b32 s0, 0
	s_add_u32 s10, s6, 0x0
	s_addc_u32 s11, s7, 0
	global_load_dwordx2 v[102:103], v99, s[10:11] offset:0
	global_load_dwordx2 v[104:105], v99, s[10:11] offset:512
	global_load_dwordx2 v[106:107], v99, s[10:11] offset:1024
	global_load_dwordx2 v[108:109], v99, s[10:11] offset:1536
	s_add_u32 s10, s4, 0x0
	s_addc_u32 s11, s5, 0
	global_load_dwordx4 v[124:127], v98, s[10:11] offset:0
	global_load_dwordx4 v[128:131], v98, s[10:11] offset:32
	global_load_dwordx4 v[132:135], v98, s[10:11] offset:64
	global_load_dwordx4 v[136:139], v98, s[10:11] offset:96
	global_load_dwordx4 v[140:143], v98, s[10:11] offset:128
	global_load_dwordx4 v[144:147], v98, s[10:11] offset:160
	global_load_dwordx4 v[148:151], v98, s[10:11] offset:192
	global_load_dwordx4 v[152:155], v98, s[10:11] offset:224
	s_add_u32 s10, s6, 0x2000
	s_addc_u32 s11, s7, 0
	global_load_dwordx2 v[110:111], v99, s[10:11] offset:0
	global_load_dwordx2 v[112:113], v99, s[10:11] offset:512
	global_load_dwordx2 v[114:115], v99, s[10:11] offset:1024
	global_load_dwordx2 v[116:117], v99, s[10:11] offset:1536
	s_add_u32 s10, s4, 0x2000
	s_addc_u32 s11, s5, 0
	global_load_dwordx4 v[156:159], v98, s[10:11] offset:0
	global_load_dwordx4 v[160:163], v98, s[10:11] offset:32
	global_load_dwordx4 v[164:167], v98, s[10:11] offset:64
	global_load_dwordx4 v[168:171], v98, s[10:11] offset:96
	global_load_dwordx4 v[172:175], v98, s[10:11] offset:128
	global_load_dwordx4 v[176:179], v98, s[10:11] offset:160
	global_load_dwordx4 v[180:183], v98, s[10:11] offset:192
	global_load_dwordx4 v[184:187], v98, s[10:11] offset:224
.Lgdn_scan_loop:
	v_cvt_pk_bf16_f32 v66, v2, v3
	v_cvt_pk_bf16_f32 v67, v4, v5
	v_cvt_pk_bf16_f32 v68, v6, v7
	v_cvt_pk_bf16_f32 v69, v8, v9
	v_cvt_pk_bf16_f32 v70, v10, v11
	v_cvt_pk_bf16_f32 v71, v12, v13
	v_cvt_pk_bf16_f32 v72, v14, v15
	v_cvt_pk_bf16_f32 v73, v16, v17
	v_cvt_pk_bf16_f32 v74, v18, v19
	v_cvt_pk_bf16_f32 v75, v20, v21
	v_cvt_pk_bf16_f32 v76, v22, v23
	v_cvt_pk_bf16_f32 v77, v24, v25
	v_cvt_pk_bf16_f32 v78, v26, v27
	v_cvt_pk_bf16_f32 v79, v28, v29
	v_cvt_pk_bf16_f32 v80, v30, v31
	v_cvt_pk_bf16_f32 v81, v32, v33
	v_cvt_pk_bf16_f32 v82, v34, v35
	v_cvt_pk_bf16_f32 v83, v36, v37
	v_cvt_pk_bf16_f32 v84, v38, v39
	v_cvt_pk_bf16_f32 v85, v40, v41
	v_cvt_pk_bf16_f32 v86, v42, v43
	v_cvt_pk_bf16_f32 v87, v44, v45
	v_cvt_pk_bf16_f32 v88, v46, v47
	v_cvt_pk_bf16_f32 v89, v48, v49
	v_cvt_pk_bf16_f32 v90, v50, v51
	v_cvt_pk_bf16_f32 v91, v52, v53
	v_cvt_pk_bf16_f32 v92, v54, v55
	v_cvt_pk_bf16_f32 v93, v56, v57
	v_cvt_pk_bf16_f32 v94, v58, v59
	v_cvt_pk_bf16_f32 v95, v60, v61
	v_cvt_pk_bf16_f32 v96, v62, v63
	v_cvt_pk_bf16_f32 v97, v64, v65
	global_store_dwordx4 v100, v[66:69], s[8:9] offset:-4096
	global_store_dwordx4 v100, v[70:73], s[8:9] offset:-3072
	global_store_dwordx4 v100, v[74:77], s[8:9] offset:-2048
	global_store_dwordx4 v100, v[78:81], s[8:9] offset:-1024
	global_store_dwordx4 v100, v[82:85], s[8:9] offset:0
	global_store_dwordx4 v100, v[86:89], s[8:9] offset:1024
	global_store_dwordx4 v100, v[90:93], s[8:9] offset:2048
	global_store_dwordx4 v100, v[94:97], s[8:9] offset:3072
	s_waitcnt vmcnt(20)
	v_lshlrev_b32_e32 v2, 16, v102
	v_and_b32_e32 v3, 0xffff0000, v102
	v_lshlrev_b32_e32 v4, 16, v103
	v_and_b32_e32 v5, 0xffff0000, v103
	v_lshlrev_b32_e32 v6, 16, v104
	v_and_b32_e32 v7, 0xffff0000, v104
	v_lshlrev_b32_e32 v8, 16, v105
	v_and_b32_e32 v9, 0xffff0000, v105
	v_lshlrev_b32_e32 v10, 16, v106
	v_and_b32_e32 v11, 0xffff0000, v106
	v_lshlrev_b32_e32 v12, 16, v107
	v_and_b32_e32 v13, 0xffff0000, v107
	v_lshlrev_b32_e32 v14, 16, v108
	v_and_b32_e32 v15, 0xffff0000, v108
	v_lshlrev_b32_e32 v16, 16, v109
	v_and_b32_e32 v17, 0xffff0000, v109
	s_nop 1
	v_mfma_f32_32x32x16_bf16 v[2:17], v[124:127], v[66:69], v[2:17]
	v_mfma_f32_32x32x16_bf16 v[2:17], v[128:131], v[70:73], v[2:17]
	v_mfma_f32_32x32x16_bf16 v[2:17], v[132:135], v[74:77], v[2:17]
	v_mfma_f32_32x32x16_bf16 v[2:17], v[136:139], v[78:81], v[2:17]
	v_mfma_f32_32x32x16_bf16 v[2:17], v[140:143], v[82:85], v[2:17]
	v_mfma_f32_32x32x16_bf16 v[2:17], v[144:147], v[86:89], v[2:17]
	v_mfma_f32_32x32x16_bf16 v[2:17], v[148:151], v[90:93], v[2:17]
	v_mfma_f32_32x32x16_bf16 v[2:17], v[152:155], v[94:97], v[2:17]
	s_add_u32 s10, s6, 0x4000
	s_addc_u32 s11, s7, 0
	global_load_dwordx2 v[102:103], v99, s[10:11] offset:0
	global_load_dwordx2 v[104:105], v99, s[10:11] offset:512
	global_load_dwordx2 v[106:107], v99, s[10:11] offset:1024
	global_load_dwordx2 v[108:109], v99, s[10:11] offset:1536
	s_add_u32 s10, s4, 0x4000
	s_addc_u32 s11, s5, 0
	global_load_dwordx4 v[124:127], v98, s[10:11] offset:0
	global_load_dwordx4 v[128:131], v98, s[10:11] offset:32
	global_load_dwordx4 v[132:135], v98, s[10:11] offset:64
	global_load_dwordx4 v[136:139], v98, s[10:11] offset:96
	global_load_dwordx4 v[140:143], v98, s[10:11] offset:128
	global_load_dwordx4 v[144:147], v98, s[10:11] offset:160
	global_load_dwordx4 v[148:151], v98, s[10:11] offset:192
	global_load_dwordx4 v[152:155], v98, s[10:11] offset:224
	s_waitcnt vmcnt(20)
	v_lshlrev_b32_e32 v18, 16, v110
	v_and_b32_e32 v19, 0xffff0000, v110
	v_lshlrev_b32_e32 v20, 16, v111
	v_and_b32_e32 v21, 0xffff0000, v111
	v_lshlrev_b32_e32 v22, 16, v112
	v_and_b32_e32 v23, 0xffff0000, v112
	v_lshlrev_b32_e32 v24, 16, v113
	v_and_b32_e32 v25, 0xffff0000, v113
	v_lshlrev_b32_e32 v26, 16, v114
	v_and_b32_e32 v27, 0xffff0000, v114
	v_lshlrev_b32_e32 v28, 16, v115
	v_and_b32_e32 v29, 0xffff0000, v115
	v_lshlrev_b32_e32 v30, 16, v116
	v_and_b32_e32 v31, 0xffff0000, v116
	v_lshlrev_b32_e32 v32, 16, v117
	v_and_b32_e32 v33, 0xffff0000, v117
	s_nop 1
	v_mfma_f32_32x32x16_bf16 v[18:33], v[156:159], v[66:69], v[18:33]
	v_mfma_f32_32x32x16_bf16 v[18:33], v[160:163], v[70:73], v[18:33]
	v_mfma_f32_32x32x16_bf16 v[18:33], v[164:167], v[74:77], v[18:33]
	v_mfma_f32_32x32x16_bf16 v[18:33], v[168:171], v[78:81], v[18:33]
	v_mfma_f32_32x32x16_bf16 v[18:33], v[172:175], v[82:85], v[18:33]
	v_mfma_f32_32x32x16_bf16 v[18:33], v[176:179], v[86:89], v[18:33]
	v_mfma_f32_32x32x16_bf16 v[18:33], v[180:183], v[90:93], v[18:33]
	v_mfma_f32_32x32x16_bf16 v[18:33], v[184:187], v[94:97], v[18:33]
	s_add_u32 s10, s6, 0x6000
	s_addc_u32 s11, s7, 0
	global_load_dwordx2 v[110:111], v99, s[10:11] offset:0
	global_load_dwordx2 v[112:113], v99, s[10:11] offset:512
	global_load_dwordx2 v[114:115], v99, s[10:11] offset:1024
	global_load_dwordx2 v[116:117], v99, s[10:11] offset:1536
	s_add_u32 s10, s4, 0x6000
	s_addc_u32 s11, s5, 0
	global_load_dwordx4 v[156:159], v98, s[10:11] offset:0
	global_load_dwordx4 v[160:163], v98, s[10:11] offset:32
	global_load_dwordx4 v[164:167], v98, s[10:11] offset:64
	global_load_dwordx4 v[168:171], v98, s[10:11] offset:96
	global_load_dwordx4 v[172:175], v98, s[10:11] offset:128
	global_load_dwordx4 v[176:179], v98, s[10:11] offset:160
	global_load_dwordx4 v[180:183], v98, s[10:11] offset:192
	global_load_dwordx4 v[184:187], v98, s[10:11] offset:224
	s_waitcnt vmcnt(12)
	v_lshlrev_b32_e32 v34, 16, v102
	v_and_b32_e32 v35, 0xffff0000, v102
	v_lshlrev_b32_e32 v36, 16, v103
	v_and_b32_e32 v37, 0xffff0000, v103
	v_lshlrev_b32_e32 v38, 16, v104
	v_and_b32_e32 v39, 0xffff0000, v104
	v_lshlrev_b32_e32 v40, 16, v105
	v_and_b32_e32 v41, 0xffff0000, v105
	v_lshlrev_b32_e32 v42, 16, v106
	v_and_b32_e32 v43, 0xffff0000, v106
	v_lshlrev_b32_e32 v44, 16, v107
	v_and_b32_e32 v45, 0xffff0000, v107
	v_lshlrev_b32_e32 v46, 16, v108
	v_and_b32_e32 v47, 0xffff0000, v108
	v_lshlrev_b32_e32 v48, 16, v109
	v_and_b32_e32 v49, 0xffff0000, v109
	s_nop 1
	v_mfma_f32_32x32x16_bf16 v[34:49], v[124:127], v[66:69], v[34:49]
	v_mfma_f32_32x32x16_bf16 v[34:49], v[128:131], v[70:73], v[34:49]
	v_mfma_f32_32x32x16_bf16 v[34:49], v[132:135], v[74:77], v[34:49]
	v_mfma_f32_32x32x16_bf16 v[34:49], v[136:139], v[78:81], v[34:49]
	v_mfma_f32_32x32x16_bf16 v[34:49], v[140:143], v[82:85], v[34:49]
	v_mfma_f32_32x32x16_bf16 v[34:49], v[144:147], v[86:89], v[34:49]
	v_mfma_f32_32x32x16_bf16 v[34:49], v[148:151], v[90:93], v[34:49]
	v_mfma_f32_32x32x16_bf16 v[34:49], v[152:155], v[94:97], v[34:49]
	s_add_u32 s10, s6, 0x8000
	s_addc_u32 s11, s7, 0
	global_load_dwordx2 v[102:103], v99, s[10:11] offset:0
	global_load_dwordx2 v[104:105], v99, s[10:11] offset:512
	global_load_dwordx2 v[106:107], v99, s[10:11] offset:1024
	global_load_dwordx2 v[108:109], v99, s[10:11] offset:1536
	s_add_u32 s10, s4, 0x8000
	s_addc_u32 s11, s5, 0
	global_load_dwordx4 v[124:127], v98, s[10:11] offset:0
	global_load_dwordx4 v[128:131], v98, s[10:11] offset:32
	global_load_dwordx4 v[132:135], v98, s[10:11] offset:64
	global_load_dwordx4 v[136:139], v98, s[10:11] offset:96
	global_load_dwordx4 v[140:143], v98, s[10:11] offset:128
	global_load_dwordx4 v[144:147], v98, s[10:11] offset:160
	global_load_dwordx4 v[148:151], v98, s[10:11] offset:192
	global_load_dwordx4 v[152:155], v98, s[10:11] offset:224
	s_waitcnt vmcnt(12)
	v_lshlrev_b32_e32 v50, 16, v110
	v_and_b32_e32 v51, 0xffff0000, v110
	v_lshlrev_b32_e32 v52, 16, v111
	v_and_b32_e32 v53, 0xffff0000, v111
	v_lshlrev_b32_e32 v54, 16, v112
	v_and_b32_e32 v55, 0xffff0000, v112
	v_lshlrev_b32_e32 v56, 16, v113
	v_and_b32_e32 v57, 0xffff0000, v113
	v_lshlrev_b32_e32 v58, 16, v114
	v_and_b32_e32 v59, 0xffff0000, v114
	v_lshlrev_b32_e32 v60, 16, v115
	v_and_b32_e32 v61, 0xffff0000, v115
	v_lshlrev_b32_e32 v62, 16, v116
	v_and_b32_e32 v63, 0xffff0000, v116
	v_lshlrev_b32_e32 v64, 16, v117
	v_and_b32_e32 v65, 0xffff0000, v117
	s_nop 1
	v_mfma_f32_32x32x16_bf16 v[50:65], v[156:159], v[66:69], v[50:65]
	v_mfma_f32_32x32x16_bf16 v[50:65], v[160:163], v[70:73], v[50:65]
	v_mfma_f32_32x32x16_bf16 v[50:65], v[164:167], v[74:77], v[50:65]
	v_mfma_f32_32x32x16_bf16 v[50:65], v[168:171], v[78:81], v[50:65]
	v_mfma_f32_32x32x16_bf16 v[50:65], v[172:175], v[82:85], v[50:65]
	v_mfma_f32_32x32x16_bf16 v[50:65], v[176:179], v[86:89], v[50:65]
	v_mfma_f32_32x32x16_bf16 v[50:65], v[180:183], v[90:93], v[50:65]
	v_mfma_f32_32x32x16_bf16 v[50:65], v[184:187], v[94:97], v[50:65]
	s_add_u32 s10, s6, 0xa000
	s_addc_u32 s11, s7, 0
	global_load_dwordx2 v[110:111], v99, s[10:11] offset:0
	global_load_dwordx2 v[112:113], v99, s[10:11] offset:512
	global_load_dwordx2 v[114:115], v99, s[10:11] offset:1024
	global_load_dwordx2 v[116:117], v99, s[10:11] offset:1536
	s_add_u32 s10, s4, 0xa000
	s_addc_u32 s11, s5, 0
	global_load_dwordx4 v[156:159], v98, s[10:11] offset:0
	global_load_dwordx4 v[160:163], v98, s[10:11] offset:32
	global_load_dwordx4 v[164:167], v98, s[10:11] offset:64
	global_load_dwordx4 v[168:171], v98, s[10:11] offset:96
	global_load_dwordx4 v[172:175], v98, s[10:11] offset:128
	global_load_dwordx4 v[176:179], v98, s[10:11] offset:160
	global_load_dwordx4 v[180:183], v98, s[10:11] offset:192
	global_load_dwordx4 v[184:187], v98, s[10:11] offset:224
	s_add_u32 s4, s4, 0x8000
	s_addc_u32 s5, s5, 0
	s_add_u32 s6, s6, 0x8000
	s_addc_u32 s7, s7, 0
	s_add_u32 s8, s8, 0x8000
	s_addc_u32 s9, s9, 0
	s_add_u32 s0, s0, 1
	s_cmp_lt_u32 s0, 32
	s_cbranch_scc1 .Lgdn_scan_loop
	s_waitcnt vmcnt(0)
	ds_read_b128 v[124:127], v101
	ds_read_b128 v[128:131], v101 offset:1024
	ds_read_b128 v[132:135], v101 offset:2048
	ds_read_b128 v[136:139], v101 offset:3072
	ds_read_b128 v[140:143], v101 offset:4096
	ds_read_b128 v[144:147], v101 offset:5120
	ds_read_b128 v[148:151], v101 offset:6144
	ds_read_b128 v[152:155], v101 offset:7168
	ds_read_b128 v[156:159], v101 offset:8192
	ds_read_b128 v[160:163], v101 offset:9216
	ds_read_b128 v[164:167], v101 offset:10240
	ds_read_b128 v[168:171], v101 offset:11264
	ds_read_b128 v[172:175], v101 offset:12288
	ds_read_b128 v[176:179], v101 offset:13312
	ds_read_b128 v[180:183], v101 offset:14336
	ds_read_b128 v[184:187], v101 offset:15360
	s_waitcnt lgkmcnt(0)
